# v73 + nt on the 16 LN2 (P9) input row loads (y2 read once)
# baseline (speedup 1.0000x reference)
; #define LAS __attribute__((address_space(3)))
; __device__ __forceinline__ size_t ytile(int row, int col) { return ((((size_t)(row >> 8) * 16) + (col >> 8)) * 256 + (row & 255)) * 256 + (col & 255); }
; template <bool LN1>
; __device__ __forceinline__ void ln_phase(Frame& F, const bf16_t* Yin, const float* ga, const float* be, const float* modf, float* stats, bf16_t* ob16, float* of32) {
;     ...
;         f32x4 ca[2], cb[2];
; #pragma unroll
;         for (int n = 0; n < 2; ++n) {
;             if (LN1) { const f32x4 sc1 = *(const f32x4*)(modf + (size_t)b * NADA + 4 * D + c0 + 4 * n) + 1.0f, sh = *(const f32x4*)(modf + (size_t)b * NADA + 3 * D + c0 + 4 * n);
;                 ca[n] = *(const f32x4*)(ga + c0 + 4 * n) * sc1; cb[n] = *(const f32x4*)(be + c0 + 4 * n) * sc1 + sh; }
;             else { ca[n] = *(const f32x4*)(ga + c0 + 4 * n); cb[n] = *(const f32x4*)(be + c0 + 4 * n); }
;         }
;         u32x4 nx[8];
; #pragma unroll
;         for (int k = 0; k < 8; ++k) nx[k] = *(const u32x4*)(Yin + ytile(rb + k, c0));
;         for (int bt = 0; bt < 8; ++bt) {
;             const int r0 = rb + 8 * bt; f32x4 v[8][2];
;             LAS f32x2* rd = red + (bt & 1) * 64;
; #pragma unroll
;             for (int k = 0; k < 8; ++k) { pg8::unpack8(nx[k], v[k][0], v[k][1]);
;                 float s = ((v[k][0][0] + v[k][0][1]) + (v[k][0][2] + v[k][0][3])) + ((v[k][1][0] + v[k][1][1]) + (v[k][1][2] + v[k][1][3]));
;                 float q = ((v[k][0][0] * v[k][0][0] + v[k][0][1] * v[k][0][1]) + (v[k][0][2] * v[k][0][2] + v[k][0][3] * v[k][0][3])) + ((v[k][1][0] * v[k][1][0] + v[k][1][1] * v[k][1][1]) + (v[k][1][2] * v[k][1][2] + v[k][1][3] * v[k][1][3]));
;                 s = wave_sum(s); q = wave_sum(q);
;                 if (lane == 0) rd[k * 8 + w] = (f32x2){s, q}; }
;             if (bt < 7) {
; #pragma unroll
;                 for (int k = 0; k < 8; ++k) nx[k] = *(const u32x4*)(Yin + ytile(r0 + 8 + k, c0));
;             }
;             __syncthreads();
; #pragma unroll
;             for (int k = 0; k < 8; ++k) {
;                 float s = 0.f, q = 0.f;
; #pragma unroll
;                 for (int ww = 0; ww < 8; ++ww) { const f32x2 p = rd[k * 8 + ww]; s += p[0]; q += p[1]; }
.LBB0_1343:
	s_ashr_i32 s2, s4, 8
	s_ashr_i32 s3, s2, 31
	s_lshl_b64 s[2:3], s[2:3], 12
	v_lshl_add_u64 v[16:17], s[2:3], 0, v[48:49]
	s_and_b32 s2, s4, 0xc0
	v_or_b32_e32 v18, s2, v16
	v_mov_b32_e32 v19, v17
	v_lshlrev_b64 v[18:19], 9, v[18:19]
	v_or3_b32 v20, s2, 1, v16
	v_mov_b32_e32 v21, v17
	v_lshl_add_u64 v[18:19], v[54:55], 0, v[18:19]
	v_lshlrev_b64 v[20:21], 9, v[20:21]
	global_load_dwordx4 v[0:3], v[50:51], off offset:16
	global_load_dwordx4 v[8:11], v[50:51], off
	s_waitcnt lgkmcnt(0)
	global_load_dwordx4 v[4:7], v[52:53], off offset:16
	global_load_dwordx4 v[12:15], v[52:53], off
	v_lshl_add_u64 v[20:21], v[54:55], 0, v[20:21]
	global_load_dwordx4 v[44:47], v[18:19], off nt
	global_load_dwordx4 v[40:43], v[20:21], off nt
	v_or3_b32 v18, s2, 2, v16
	v_mov_b32_e32 v19, v17
	v_lshlrev_b64 v[18:19], 9, v[18:19]
	v_or3_b32 v20, s2, 3, v16
	v_mov_b32_e32 v21, v17
	v_lshl_add_u64 v[18:19], v[54:55], 0, v[18:19]
	v_lshlrev_b64 v[20:21], 9, v[20:21]
	v_lshl_add_u64 v[20:21], v[54:55], 0, v[20:21]
	global_load_dwordx4 v[36:39], v[18:19], off nt
	global_load_dwordx4 v[32:35], v[20:21], off nt
	v_or3_b32 v18, s2, 4, v16
	v_mov_b32_e32 v19, v17
	v_lshlrev_b64 v[18:19], 9, v[18:19]
	v_or3_b32 v20, s2, 5, v16
	v_mov_b32_e32 v21, v17
	v_lshl_add_u64 v[18:19], v[54:55], 0, v[18:19]
	v_lshlrev_b64 v[20:21], 9, v[20:21]
	v_lshl_add_u64 v[20:21], v[54:55], 0, v[20:21]
	global_load_dwordx4 v[28:31], v[18:19], off nt
	global_load_dwordx4 v[24:27], v[20:21], off nt
	v_or3_b32 v18, s2, 6, v16
	v_mov_b32_e32 v19, v17
	v_lshlrev_b64 v[18:19], 9, v[18:19]
	v_or3_b32 v16, s2, 7, v16
	v_lshl_add_u64 v[60:61], v[54:55], 0, v[18:19]
	v_lshlrev_b64 v[16:17], 9, v[16:17]
	v_lshl_add_u64 v[62:63], v[54:55], 0, v[16:17]
	global_load_dwordx4 v[20:23], v[60:61], off nt
	global_load_dwordx4 v[16:19], v[62:63], off nt
	v_mov_b64_e32 v[60:61], v[58:59]
	s_mov_b32 s7, 0
	s_mov_b32 s15, 0
	s_branch .LBB0_1345
.LBB0_1344:
	s_or_b64 exec, exec, s[2:3]
	s_add_i32 s16, s4, s15
	s_add_i32 s18, s16, 8
	s_ashr_i32 s2, s18, 8
	s_ashr_i32 s3, s2, 31
	s_lshl_b64 s[2:3], s[2:3], 12
	v_lshl_add_u64 v[16:17], s[2:3], 0, v[48:49]
	s_and_b32 s2, s18, 0xf8
	s_waitcnt lgkmcnt(1)
	v_or_b32_e32 v18, s2, v16
	s_waitcnt lgkmcnt(0)
	v_mov_b32_e32 v19, v17
	v_lshlrev_b64 v[18:19], 9, v[18:19]
	v_or3_b32 v20, s2, 1, v16
	v_mov_b32_e32 v21, v17
	v_lshl_add_u64 v[18:19], v[54:55], 0, v[18:19]
	v_lshlrev_b64 v[20:21], 9, v[20:21]
	v_lshl_add_u64 v[20:21], v[54:55], 0, v[20:21]
	global_load_dwordx4 v[44:47], v[18:19], off nt
	global_load_dwordx4 v[40:43], v[20:21], off nt
	v_or3_b32 v18, s2, 2, v16
	v_mov_b32_e32 v19, v17
	v_lshlrev_b64 v[18:19], 9, v[18:19]
	v_or3_b32 v20, s2, 3, v16
	v_mov_b32_e32 v21, v17
	v_lshl_add_u64 v[18:19], v[54:55], 0, v[18:19]
	v_lshlrev_b64 v[20:21], 9, v[20:21]
	v_lshl_add_u64 v[20:21], v[54:55], 0, v[20:21]
	global_load_dwordx4 v[36:39], v[18:19], off nt
	global_load_dwordx4 v[32:35], v[20:21], off nt
	v_or3_b32 v18, s2, 4, v16
	v_mov_b32_e32 v19, v17
	v_lshlrev_b64 v[18:19], 9, v[18:19]
	v_or3_b32 v20, s2, 5, v16
	v_mov_b32_e32 v21, v17
	v_lshl_add_u64 v[18:19], v[54:55], 0, v[18:19]
	v_lshlrev_b64 v[20:21], 9, v[20:21]
	v_lshl_add_u64 v[20:21], v[54:55], 0, v[20:21]
	global_load_dwordx4 v[28:31], v[18:19], off nt
	global_load_dwordx4 v[24:27], v[20:21], off nt
	v_or3_b32 v18, s2, 6, v16
	v_mov_b32_e32 v19, v17
	v_or3_b32 v16, s2, 7, v16
	v_lshlrev_b64 v[18:19], 9, v[18:19]
	v_lshlrev_b64 v[16:17], 9, v[16:17]
	v_lshl_add_u64 v[18:19], v[54:55], 0, v[18:19]
	v_lshl_add_u64 v[16:17], v[54:55], 0, v[16:17]
	v_mov_b32_e32 v63, s17
	global_load_dwordx4 v[20:23], v[18:19], off nt
	s_nop 0
	global_load_dwordx4 v[16:19], v[16:17], off nt
	s_barrier
	ds_read_b128 v[198:201], v63
	ds_read_b128 v[202:205], v63 offset:16
	ds_read_b128 v[206:209], v63 offset:32
	ds_read_b128 v[210:213], v63 offset:48
	s_add_i32 s15, s15, 8
	s_waitcnt lgkmcnt(3)
	v_pk_add_f32 v[198:199], v[198:199], 0 op_sel_hi:[1,0]
	s_add_i32 s7, s7, 64
	v_pk_add_f32 v[198:199], v[198:199], v[200:201]
	s_waitcnt lgkmcnt(2)
	v_pk_add_f32 v[198:199], v[198:199], v[202:203]
	s_nop 0
	v_pk_add_f32 v[198:199], v[198:199], v[204:205]
	s_waitcnt lgkmcnt(1)
	v_pk_add_f32 v[198:199], v[198:199], v[206:207]
	s_nop 0
	v_pk_add_f32 v[198:199], v[198:199], v[208:209]
	s_waitcnt lgkmcnt(0)
	v_pk_add_f32 v[198:199], v[198:199], v[210:211]
	s_nop 0
	v_pk_add_f32 v[198:199], v[198:199], v[212:213]
	s_nop 0
	v_pk_mul_f32 v[202:203], v[198:199], s[10:11] op_sel_hi:[1,0]
	s_nop 0
	v_fma_f32 v65, -v202, v202, v203
	v_max_f32_e32 v65, 0, v65
	v_add_f32_e32 v65, 0x3727c5ac, v65
	v_mul_f32_e32 v67, 0x4f800000, v65
	v_cmp_gt_f32_e32 vcc, s5, v65
	v_sub_f32_e32 v187, v188, v202
	v_sub_f32_e32 v186, v186, v202
	v_cndmask_b32_e32 v65, v65, v67, vcc
	v_sqrt_f32_e32 v67, v65
	v_sub_f32_e32 v183, v184, v202
	v_sub_f32_e32 v182, v182, v202
	v_sub_f32_e32 v207, v180, v202
	v_add_u32_e32 v69, -1, v67
	v_fma_f32 v71, -v69, v67, v65
	v_cmp_ge_f32_e64 s[2:3], 0, v71
	v_add_u32_e32 v71, 1, v67
	v_sub_f32_e32 v206, v178, v202
	v_cndmask_b32_e64 v69, v67, v69, s[2:3]
	v_fma_f32 v67, -v71, v67, v65
	v_cmp_lt_f32_e64 s[2:3], 0, v67
	ds_read_b128 v[178:181], v63 offset:64
	v_sub_f32_e32 v149, v168, v202
	v_cndmask_b32_e64 v67, v69, v71, s[2:3]
	v_mul_f32_e32 v69, 0x37800000, v67
	v_cndmask_b32_e32 v67, v67, v69, vcc
	v_cmp_class_f32_e32 vcc, v65, v196
	s_waitcnt lgkmcnt(0)
; __device__ __forceinline__ u32x4 pack8f(f32x4 lo, f32x4 hi) { u32x4 w; w.x = cvtpk(lo[0], lo[1]); w.y = cvtpk(lo[2], lo[3]); w.z = cvtpk(hi[0], hi[1]); w.w = cvtpk(hi[2], hi[3]); return w; }
; template <bool LN1>
; __device__ __forceinline__ void ln_phase(Frame& F, const bf16_t* Yin, const float* ga, const float* be, const float* modf, float* stats, bf16_t* ob16, float* of32) {
;     ...
; #pragma unroll
;             for (int k = 0; k < 8; ++k) {
;                 float s = 0.f, q = 0.f;
; #pragma unroll
;                 for (int ww = 0; ww < 8; ++ww) { const f32x2 p = rd[k * 8 + ww]; s += p[0]; q += p[1]; }
;                 const float mean = s * (1.0f / D), var = fmaxf(q * (1.0f / D) - mean * mean, 0.f), rstd = 1.0f / sqrtf(var + 1e-5f);
;                 const size_t ro = (size_t)(r0 + k) * D + c0;
;                 if (LN1) { if (w == 0 && lane == 0) *(f32x2*)(stats + (size_t)(r0 + k) * 2) = (f32x2){mean, rstd};
;                     const int row = r0 + k; const size_t bo = ((((size_t)(row >> 8) * (D / 64)) + (c0 >> 6)) * 256 + (row & 255)) * 64 + (c0 & 63);
;                     *(u32x4*)(ob16 + bo) = pg8::pack8f((v[k][0] - mean) * rstd * ca[0] + cb[0], (v[k][1] - mean) * rstd * ca[1] + cb[1]); }
;                 else { *(f32x4*)(of32 + ro) = (v[k][0] - mean) * rstd * ca[0] + cb[0]; *(f32x4*)(of32 + ro + 4) = (v[k][1] - mean) * rstd * ca[1] + cb[1]; }
	v_pk_add_f32 v[168:169], v[178:179], 0 op_sel_hi:[1,0]
	v_sub_f32_e32 v148, v148, v202
	v_cndmask_b32_e32 v65, v67, v65, vcc
	v_div_scale_f32 v67, s[2:3], v65, v65, 1.0
	v_rcp_f32_e32 v69, v67
	v_pk_add_f32 v[168:169], v[168:169], v[180:181]
	v_fma_f32 v71, -v67, v69, 1.0
	v_fmac_f32_e32 v69, v71, v69
	v_div_scale_f32 v71, vcc, 1.0, v65, 1.0
	v_mul_f32_e32 v73, v71, v69
	v_fma_f32 v75, -v67, v73, v71
	v_fmac_f32_e32 v73, v75, v69
	v_fma_f32 v67, -v67, v73, v71
	v_div_fmas_f32 v67, v67, v69, v73
	v_div_fixup_f32 v204, v67, v65, 1.0
	v_pk_mul_f32 v[182:183], v[182:183], v[204:205] op_sel_hi:[1,0]
	v_pk_mul_f32 v[184:185], v[186:187], v[204:205] op_sel_hi:[1,0]
	v_pk_fma_f32 v[182:183], v[8:9], v[182:183], v[12:13]
	v_pk_fma_f32 v[184:185], v[10:11], v[184:185], v[14:15]
	global_store_dwordx4 v[60:61], v[182:185], off offset:-16
	ds_read_b128 v[182:185], v63 offset:80
	ds_read_b128 v[186:189], v63 offset:96
	ds_read_b128 v[198:201], v63 offset:112
	v_pk_mul_f32 v[148:149], v[148:149], v[204:205] op_sel_hi:[1,0]
	s_waitcnt lgkmcnt(2)
	v_pk_add_f32 v[168:169], v[168:169], v[182:183]
	s_nop 0
	v_pk_add_f32 v[168:169], v[168:169], v[184:185]
	v_pk_fma_f32 v[178:179], v[0:1], v[148:149], v[4:5]
	s_waitcnt lgkmcnt(1)
	v_pk_add_f32 v[168:169], v[168:169], v[186:187]
	s_nop 0
	v_pk_add_f32 v[168:169], v[168:169], v[188:189]
	s_waitcnt lgkmcnt(0)
	v_pk_add_f32 v[168:169], v[168:169], v[198:199]
	s_nop 0
	v_pk_add_f32 v[168:169], v[168:169], v[200:201]
	s_nop 0
	v_pk_mul_f32 v[182:183], v[168:169], s[10:11] op_sel_hi:[1,0]
	v_pk_mul_f32 v[168:169], v[206:207], v[204:205] op_sel_hi:[1,0]
	v_fma_f32 v65, -v182, v182, v183
	v_max_f32_e32 v65, 0, v65
	v_add_f32_e32 v65, 0x3727c5ac, v65
	v_mul_f32_e32 v67, 0x4f800000, v65
	v_cmp_gt_f32_e32 vcc, s5, v65
	v_pk_fma_f32 v[180:181], v[2:3], v[168:169], v[6:7]
	v_sub_f32_e32 v169, v176, v182
	v_cndmask_b32_e32 v65, v65, v67, vcc
	v_sqrt_f32_e32 v67, v65
	v_sub_f32_e32 v168, v174, v182
	v_sub_f32_e32 v171, v172, v182
	v_sub_f32_e32 v170, v170, v182
	v_add_u32_e32 v69, -1, v67
	v_fma_f32 v71, -v69, v67, v65
	v_cmp_ge_f32_e64 s[2:3], 0, v71
	v_add_u32_e32 v71, 1, v67
	v_sub_f32_e32 v185, v166, v182
	v_cndmask_b32_e64 v69, v67, v69, s[2:3]
	v_fma_f32 v67, -v71, v67, v65
	v_cmp_lt_f32_e64 s[2:3], 0, v67
	v_sub_f32_e32 v184, v164, v182
	ds_read_b128 v[164:167], v63 offset:128
	v_cndmask_b32_e64 v67, v69, v71, s[2:3]
	v_mul_f32_e32 v69, 0x37800000, v67
	v_cndmask_b32_e32 v67, v67, v69, vcc
	v_cmp_class_f32_e32 vcc, v65, v196
	global_store_dwordx4 v[60:61], v[178:181], off
	v_sub_f32_e32 v135, v154, v182
	v_cndmask_b32_e32 v65, v67, v65, vcc
	v_div_scale_f32 v67, s[2:3], v65, v65, 1.0
	v_rcp_f32_e32 v69, v67
	s_add_i32 s2, s16, 1
	s_ashr_i32 s3, s2, 31
	s_lshl_b64 s[2:3], s[2:3], 14
	v_fma_f32 v71, -v67, v69, 1.0
	v_fmac_f32_e32 v69, v71, v69
	v_div_scale_f32 v71, vcc, 1.0, v65, 1.0
	v_mul_f32_e32 v73, v71, v69
	v_fma_f32 v75, -v67, v73, v71
	v_fmac_f32_e32 v73, v75, v69
	v_fma_f32 v67, -v67, v73, v71
	v_div_fmas_f32 v67, v67, v69, v73
	v_div_fixup_f32 v148, v67, v65, 1.0
	v_pk_mul_f32 v[172:173], v[170:171], v[148:149] op_sel_hi:[1,0]
	v_pk_mul_f32 v[168:169], v[168:169], v[148:149] op_sel_hi:[1,0]
	v_lshl_add_u64 v[180:181], v[56:57], 0, s[2:3]
	v_pk_fma_f32 v[170:171], v[10:11], v[168:169], v[14:15]
	v_pk_fma_f32 v[168:169], v[8:9], v[172:173], v[12:13]
	global_store_dwordx4 v[180:181], v[168:171], off
	ds_read_b128 v[168:171], v63 offset:144
	ds_read_b128 v[172:175], v63 offset:160
	ds_read_b128 v[176:179], v63 offset:176
	s_waitcnt lgkmcnt(3)
	v_pk_add_f32 v[154:155], v[164:165], 0 op_sel_hi:[1,0]
	v_sub_f32_e32 v134, v134, v182
	v_pk_add_f32 v[154:155], v[154:155], v[166:167]
	v_pk_mul_f32 v[134:135], v[134:135], v[148:149] op_sel_hi:[1,0]
	s_waitcnt lgkmcnt(2)
	v_pk_add_f32 v[154:155], v[154:155], v[168:169]
	v_pk_mul_f32 v[148:149], v[184:185], v[148:149] op_sel_hi:[1,0]
	v_pk_add_f32 v[154:155], v[154:155], v[170:171]
	v_pk_fma_f32 v[166:167], v[2:3], v[148:149], v[6:7]
	s_waitcnt lgkmcnt(1)
	v_pk_add_f32 v[154:155], v[154:155], v[172:173]
	v_pk_fma_f32 v[164:165], v[0:1], v[134:135], v[4:5]
	v_pk_add_f32 v[154:155], v[154:155], v[174:175]
	global_store_dwordx4 v[180:181], v[164:167], off offset:16
	s_waitcnt lgkmcnt(0)
	v_pk_add_f32 v[154:155], v[154:155], v[176:177]
	v_lshl_add_u64 v[60:61], v[60:61], 0, s[12:13]
	v_pk_add_f32 v[154:155], v[154:155], v[178:179]
	s_nop 0
	v_pk_mul_f32 v[168:169], v[154:155], s[10:11] op_sel_hi:[1,0]
	s_nop 0
	v_fma_f32 v65, -v168, v168, v169
	v_max_f32_e32 v65, 0, v65
	v_add_f32_e32 v65, 0x3727c5ac, v65
	v_mul_f32_e32 v67, 0x4f800000, v65
	v_cmp_gt_f32_e32 vcc, s5, v65
	v_sub_f32_e32 v149, v162, v168
	v_sub_f32_e32 v148, v160, v168
	v_cndmask_b32_e32 v65, v65, v67, vcc
	v_sqrt_f32_e32 v67, v65
	v_sub_f32_e32 v155, v158, v168
	v_sub_f32_e32 v154, v156, v168
	v_sub_f32_e32 v166, v150, v168
	v_add_u32_e32 v69, -1, v67
	v_fma_f32 v71, -v69, v67, v65
	v_cmp_ge_f32_e64 s[2:3], 0, v71
	v_add_u32_e32 v71, 1, v67
	v_sub_f32_e32 v167, v152, v168
	v_cndmask_b32_e64 v69, v67, v69, s[2:3]
	v_fma_f32 v67, -v71, v67, v65
	v_cmp_lt_f32_e64 s[2:3], 0, v67
	v_sub_f32_e32 v119, v138, v168
	v_sub_f32_e32 v118, v118, v168
	v_cndmask_b32_e64 v67, v69, v71, s[2:3]
	v_mul_f32_e32 v69, 0x37800000, v67
	v_cndmask_b32_e32 v67, v67, v69, vcc
	v_cmp_class_f32_e32 vcc, v65, v196
	s_nop 1
	v_cndmask_b32_e32 v65, v67, v65, vcc
	v_div_scale_f32 v67, s[2:3], v65, v65, 1.0
	v_rcp_f32_e32 v69, v67
	s_add_i32 s2, s16, 2
	s_ashr_i32 s3, s2, 31
	s_lshl_b64 s[2:3], s[2:3], 14
	v_fma_f32 v71, -v67, v69, 1.0
	v_fmac_f32_e32 v69, v71, v69
	v_div_scale_f32 v71, vcc, 1.0, v65, 1.0
	v_mul_f32_e32 v73, v71, v69
	v_fma_f32 v75, -v67, v73, v71
	v_fmac_f32_e32 v73, v75, v69
	v_fma_f32 v67, -v67, v73, v71
	v_div_fmas_f32 v67, v67, v69, v73
	v_div_fixup_f32 v134, v67, v65, 1.0
	v_pk_mul_f32 v[148:149], v[148:149], v[134:135] op_sel_hi:[1,0]
	v_pk_mul_f32 v[154:155], v[154:155], v[134:135] op_sel_hi:[1,0]
	v_pk_fma_f32 v[156:157], v[10:11], v[148:149], v[14:15]
	ds_read_b128 v[148:151], v63 offset:192
	v_pk_fma_f32 v[154:155], v[8:9], v[154:155], v[12:13]
	v_lshl_add_u64 v[164:165], v[56:57], 0, s[2:3]
	global_store_dwordx4 v[164:165], v[154:157], off
	ds_read_b128 v[152:155], v63 offset:208
	ds_read_b128 v[156:159], v63 offset:224
	ds_read_b128 v[160:163], v63 offset:240
	s_waitcnt lgkmcnt(3)
; __device__ __forceinline__ u32x4 pack8f(f32x4 lo, f32x4 hi) { u32x4 w; w.x = cvtpk(lo[0], lo[1]); w.y = cvtpk(lo[2], lo[3]); w.z = cvtpk(hi[0], hi[1]); w.w = cvtpk(hi[2], hi[3]); return w; }
; template <bool LN1>
; __device__ __forceinline__ void ln_phase(Frame& F, const bf16_t* Yin, const float* ga, const float* be, const float* modf, float* stats, bf16_t* ob16, float* of32) {
;     ...
; #pragma unroll
;             for (int k = 0; k < 8; ++k) {
;                 float s = 0.f, q = 0.f;
; #pragma unroll
;                 for (int ww = 0; ww < 8; ++ww) { const f32x2 p = rd[k * 8 + ww]; s += p[0]; q += p[1]; }
;                 const float mean = s * (1.0f / D), var = fmaxf(q * (1.0f / D) - mean * mean, 0.f), rstd = 1.0f / sqrtf(var + 1e-5f);
;                 const size_t ro = (size_t)(r0 + k) * D + c0;
;                 if (LN1) { if (w == 0 && lane == 0) *(f32x2*)(stats + (size_t)(r0 + k) * 2) = (f32x2){mean, rstd};
;                     const int row = r0 + k; const size_t bo = ((((size_t)(row >> 8) * (D / 64)) + (c0 >> 6)) * 256 + (row & 255)) * 64 + (c0 & 63);
;                     *(u32x4*)(ob16 + bo) = pg8::pack8f((v[k][0] - mean) * rstd * ca[0] + cb[0], (v[k][1] - mean) * rstd * ca[1] + cb[1]); }
;                 else { *(f32x4*)(of32 + ro) = (v[k][0] - mean) * rstd * ca[0] + cb[0]; *(f32x4*)(of32 + ro + 4) = (v[k][1] - mean) * rstd * ca[1] + cb[1]; }
	v_pk_add_f32 v[138:139], v[148:149], 0 op_sel_hi:[1,0]
	v_pk_mul_f32 v[118:119], v[118:119], v[134:135] op_sel_hi:[1,0]
	v_pk_add_f32 v[138:139], v[138:139], v[150:151]
	v_pk_mul_f32 v[134:135], v[166:167], v[134:135] op_sel_hi:[1,0]
	s_waitcnt lgkmcnt(2)
	v_pk_add_f32 v[138:139], v[138:139], v[152:153]
	v_pk_fma_f32 v[150:151], v[2:3], v[134:135], v[6:7]
	v_pk_add_f32 v[138:139], v[138:139], v[154:155]
	v_pk_fma_f32 v[148:149], v[0:1], v[118:119], v[4:5]
	s_waitcnt lgkmcnt(1)
	v_pk_add_f32 v[138:139], v[138:139], v[156:157]
	global_store_dwordx4 v[164:165], v[148:151], off offset:16
	v_pk_add_f32 v[138:139], v[138:139], v[158:159]
	s_waitcnt lgkmcnt(0)
	v_pk_add_f32 v[138:139], v[138:139], v[160:161]
	s_nop 0
	v_pk_add_f32 v[138:139], v[138:139], v[162:163]
	s_nop 0
	v_pk_mul_f32 v[152:153], v[138:139], s[10:11] op_sel_hi:[1,0]
	s_nop 0
	v_fma_f32 v65, -v152, v152, v153
	v_max_f32_e32 v65, 0, v65
	v_add_f32_e32 v65, 0x3727c5ac, v65
	v_mul_f32_e32 v67, 0x4f800000, v65
	v_cmp_gt_f32_e32 vcc, s5, v65
	v_sub_f32_e32 v135, v146, v152
	v_sub_f32_e32 v134, v144, v152
	v_cndmask_b32_e32 v65, v65, v67, vcc
	v_sqrt_f32_e32 v67, v65
	v_sub_f32_e32 v139, v142, v152
	v_sub_f32_e32 v138, v140, v152
	v_sub_f32_e32 v150, v132, v152
	v_add_u32_e32 v69, -1, v67
	v_fma_f32 v71, -v69, v67, v65
	v_cmp_ge_f32_e64 s[2:3], 0, v71
	v_add_u32_e32 v71, 1, v67
	v_sub_f32_e32 v151, v136, v152
	v_cndmask_b32_e64 v69, v67, v69, s[2:3]
	v_fma_f32 v67, -v71, v67, v65
	v_cmp_lt_f32_e64 s[2:3], 0, v67
	v_sub_f32_e32 v103, v122, v152
	v_sub_f32_e32 v102, v102, v152
	v_cndmask_b32_e64 v67, v69, v71, s[2:3]
	v_mul_f32_e32 v69, 0x37800000, v67
	v_cndmask_b32_e32 v67, v67, v69, vcc
	v_cmp_class_f32_e32 vcc, v65, v196
	s_nop 1
	v_cndmask_b32_e32 v65, v67, v65, vcc
	v_div_scale_f32 v67, s[2:3], v65, v65, 1.0
	v_rcp_f32_e32 v69, v67
	s_add_i32 s2, s16, 3
	s_ashr_i32 s3, s2, 31
	s_lshl_b64 s[2:3], s[2:3], 14
	v_fma_f32 v71, -v67, v69, 1.0
	v_fmac_f32_e32 v69, v71, v69
	v_div_scale_f32 v71, vcc, 1.0, v65, 1.0
	v_mul_f32_e32 v73, v71, v69
	v_fma_f32 v75, -v67, v73, v71
	v_fmac_f32_e32 v73, v75, v69
	v_fma_f32 v67, -v67, v73, v71
	v_div_fmas_f32 v67, v67, v69, v73
	v_div_fixup_f32 v118, v67, v65, 1.0
	v_pk_mul_f32 v[134:135], v[134:135], v[118:119] op_sel_hi:[1,0]
	v_pk_mul_f32 v[138:139], v[138:139], v[118:119] op_sel_hi:[1,0]
	v_pk_fma_f32 v[140:141], v[10:11], v[134:135], v[14:15]
	ds_read_b128 v[132:135], v63 offset:256
	v_pk_fma_f32 v[138:139], v[8:9], v[138:139], v[12:13]
	v_lshl_add_u64 v[148:149], v[56:57], 0, s[2:3]
	global_store_dwordx4 v[148:149], v[138:141], off
	ds_read_b128 v[136:139], v63 offset:272
	ds_read_b128 v[140:143], v63 offset:288
	ds_read_b128 v[144:147], v63 offset:304
	s_waitcnt lgkmcnt(3)
	v_pk_add_f32 v[122:123], v[132:133], 0 op_sel_hi:[1,0]
	v_pk_mul_f32 v[102:103], v[102:103], v[118:119] op_sel_hi:[1,0]
	v_pk_add_f32 v[122:123], v[122:123], v[134:135]
	v_pk_mul_f32 v[118:119], v[150:151], v[118:119] op_sel_hi:[1,0]
	s_waitcnt lgkmcnt(2)
	v_pk_add_f32 v[122:123], v[122:123], v[136:137]
	v_pk_fma_f32 v[134:135], v[2:3], v[118:119], v[6:7]
	v_pk_add_f32 v[122:123], v[122:123], v[138:139]
	v_pk_fma_f32 v[132:133], v[0:1], v[102:103], v[4:5]
	s_waitcnt lgkmcnt(1)
	v_pk_add_f32 v[122:123], v[122:123], v[140:141]
	global_store_dwordx4 v[148:149], v[132:135], off offset:16
	v_pk_add_f32 v[122:123], v[122:123], v[142:143]
	s_waitcnt lgkmcnt(0)
	v_pk_add_f32 v[122:123], v[122:123], v[144:145]
	s_nop 0
	v_pk_add_f32 v[122:123], v[122:123], v[146:147]
	s_nop 0
	v_pk_mul_f32 v[136:137], v[122:123], s[10:11] op_sel_hi:[1,0]
	s_nop 0
	v_fma_f32 v65, -v136, v136, v137
	v_max_f32_e32 v65, 0, v65
	v_add_f32_e32 v65, 0x3727c5ac, v65
	v_mul_f32_e32 v67, 0x4f800000, v65
	v_cmp_gt_f32_e32 vcc, s5, v65
	v_sub_f32_e32 v119, v130, v136
	v_sub_f32_e32 v118, v128, v136
	v_cndmask_b32_e32 v65, v65, v67, vcc
	v_sqrt_f32_e32 v67, v65
	v_sub_f32_e32 v123, v126, v136
	v_sub_f32_e32 v122, v124, v136
	v_sub_f32_e32 v134, v116, v136
	v_add_u32_e32 v69, -1, v67
	v_fma_f32 v71, -v69, v67, v65
	v_cmp_ge_f32_e64 s[2:3], 0, v71
	v_add_u32_e32 v71, 1, v67
	v_sub_f32_e32 v135, v120, v136
	v_cndmask_b32_e64 v69, v67, v69, s[2:3]
	v_fma_f32 v67, -v71, v67, v65
	v_cmp_lt_f32_e64 s[2:3], 0, v67
	v_sub_f32_e32 v87, v106, v136
	v_sub_f32_e32 v86, v86, v136
	v_cndmask_b32_e64 v67, v69, v71, s[2:3]
	v_mul_f32_e32 v69, 0x37800000, v67
	v_cndmask_b32_e32 v67, v67, v69, vcc
	v_cmp_class_f32_e32 vcc, v65, v196
	s_nop 1
	v_cndmask_b32_e32 v65, v67, v65, vcc
	v_div_scale_f32 v67, s[2:3], v65, v65, 1.0
	v_rcp_f32_e32 v69, v67
	s_add_i32 s2, s16, 4
	s_ashr_i32 s3, s2, 31
	s_lshl_b64 s[2:3], s[2:3], 14
	v_fma_f32 v71, -v67, v69, 1.0
	v_fmac_f32_e32 v69, v71, v69
	v_div_scale_f32 v71, vcc, 1.0, v65, 1.0
	v_mul_f32_e32 v73, v71, v69
	v_fma_f32 v75, -v67, v73, v71
	v_fmac_f32_e32 v73, v75, v69
	v_fma_f32 v67, -v67, v73, v71
	v_div_fmas_f32 v67, v67, v69, v73
	v_div_fixup_f32 v102, v67, v65, 1.0
	v_pk_mul_f32 v[118:119], v[118:119], v[102:103] op_sel_hi:[1,0]
	v_pk_mul_f32 v[122:123], v[122:123], v[102:103] op_sel_hi:[1,0]
	v_pk_fma_f32 v[124:125], v[10:11], v[118:119], v[14:15]
	ds_read_b128 v[116:119], v63 offset:320
	v_pk_fma_f32 v[122:123], v[8:9], v[122:123], v[12:13]
	v_lshl_add_u64 v[132:133], v[56:57], 0, s[2:3]
	global_store_dwordx4 v[132:133], v[122:125], off
	ds_read_b128 v[120:123], v63 offset:336
	ds_read_b128 v[124:127], v63 offset:352
	ds_read_b128 v[128:131], v63 offset:368
	s_waitcnt lgkmcnt(3)
	v_pk_add_f32 v[106:107], v[116:117], 0 op_sel_hi:[1,0]
	v_pk_mul_f32 v[86:87], v[86:87], v[102:103] op_sel_hi:[1,0]
	v_pk_add_f32 v[106:107], v[106:107], v[118:119]
	v_pk_mul_f32 v[102:103], v[134:135], v[102:103] op_sel_hi:[1,0]
	s_waitcnt lgkmcnt(2)
; __device__ __forceinline__ u32x4 pack8f(f32x4 lo, f32x4 hi) { u32x4 w; w.x = cvtpk(lo[0], lo[1]); w.y = cvtpk(lo[2], lo[3]); w.z = cvtpk(hi[0], hi[1]); w.w = cvtpk(hi[2], hi[3]); return w; }
; template <bool LN1>
; __device__ __forceinline__ void ln_phase(Frame& F, const bf16_t* Yin, const float* ga, const float* be, const float* modf, float* stats, bf16_t* ob16, float* of32) {
;     ...
; #pragma unroll
;             for (int k = 0; k < 8; ++k) {
;                 float s = 0.f, q = 0.f;
; #pragma unroll
;                 for (int ww = 0; ww < 8; ++ww) { const f32x2 p = rd[k * 8 + ww]; s += p[0]; q += p[1]; }
;                 const float mean = s * (1.0f / D), var = fmaxf(q * (1.0f / D) - mean * mean, 0.f), rstd = 1.0f / sqrtf(var + 1e-5f);
;                 const size_t ro = (size_t)(r0 + k) * D + c0;
;                 if (LN1) { if (w == 0 && lane == 0) *(f32x2*)(stats + (size_t)(r0 + k) * 2) = (f32x2){mean, rstd};
;                     const int row = r0 + k; const size_t bo = ((((size_t)(row >> 8) * (D / 64)) + (c0 >> 6)) * 256 + (row & 255)) * 64 + (c0 & 63);
;                     *(u32x4*)(ob16 + bo) = pg8::pack8f((v[k][0] - mean) * rstd * ca[0] + cb[0], (v[k][1] - mean) * rstd * ca[1] + cb[1]); }
;                 else { *(f32x4*)(of32 + ro) = (v[k][0] - mean) * rstd * ca[0] + cb[0]; *(f32x4*)(of32 + ro + 4) = (v[k][1] - mean) * rstd * ca[1] + cb[1]; }
	v_pk_add_f32 v[106:107], v[106:107], v[120:121]
	v_pk_fma_f32 v[118:119], v[2:3], v[102:103], v[6:7]
	v_pk_add_f32 v[106:107], v[106:107], v[122:123]
	v_pk_fma_f32 v[116:117], v[0:1], v[86:87], v[4:5]
	s_waitcnt lgkmcnt(1)
	v_pk_add_f32 v[106:107], v[106:107], v[124:125]
	global_store_dwordx4 v[132:133], v[116:119], off offset:16
	v_pk_add_f32 v[106:107], v[106:107], v[126:127]
	s_waitcnt lgkmcnt(0)
	v_pk_add_f32 v[106:107], v[106:107], v[128:129]
	s_nop 0
	v_pk_add_f32 v[106:107], v[106:107], v[130:131]
	s_nop 0
	v_pk_mul_f32 v[120:121], v[106:107], s[10:11] op_sel_hi:[1,0]
	s_nop 0
	v_fma_f32 v65, -v120, v120, v121
	v_max_f32_e32 v65, 0, v65
	v_add_f32_e32 v65, 0x3727c5ac, v65
	v_mul_f32_e32 v67, 0x4f800000, v65
	v_cmp_gt_f32_e32 vcc, s5, v65
	v_sub_f32_e32 v103, v114, v120
	v_sub_f32_e32 v102, v112, v120
	v_cndmask_b32_e32 v65, v65, v67, vcc
	v_sqrt_f32_e32 v67, v65
	v_sub_f32_e32 v107, v110, v120
	v_sub_f32_e32 v106, v108, v120
	v_sub_f32_e32 v118, v100, v120
	v_add_u32_e32 v69, -1, v67
	v_fma_f32 v71, -v69, v67, v65
	v_cmp_ge_f32_e64 s[2:3], 0, v71
	v_add_u32_e32 v71, 1, v67
	v_sub_f32_e32 v119, v104, v120
	v_cndmask_b32_e64 v69, v67, v69, s[2:3]
	v_fma_f32 v67, -v71, v67, v65
	v_cmp_lt_f32_e64 s[2:3], 0, v67
	v_sub_f32_e32 v70, v70, v120
	s_nop 0
	v_cndmask_b32_e64 v67, v69, v71, s[2:3]
	v_mul_f32_e32 v69, 0x37800000, v67
	v_cndmask_b32_e32 v67, v67, v69, vcc
	v_cmp_class_f32_e32 vcc, v65, v196
	s_nop 1
	v_cndmask_b32_e32 v65, v67, v65, vcc
	v_div_scale_f32 v67, s[2:3], v65, v65, 1.0
	v_rcp_f32_e32 v69, v67
	s_add_i32 s2, s16, 5
	s_ashr_i32 s3, s2, 31
	s_lshl_b64 s[2:3], s[2:3], 14
	v_fma_f32 v71, -v67, v69, 1.0
	v_fmac_f32_e32 v69, v71, v69
	v_div_scale_f32 v71, vcc, 1.0, v65, 1.0
	v_mul_f32_e32 v73, v71, v69
	v_fma_f32 v75, -v67, v73, v71
	v_fmac_f32_e32 v73, v75, v69
	v_fma_f32 v67, -v67, v73, v71
	v_div_fmas_f32 v67, v67, v69, v73
	v_div_fixup_f32 v86, v67, v65, 1.0
	v_pk_mul_f32 v[102:103], v[102:103], v[86:87] op_sel_hi:[1,0]
	v_pk_mul_f32 v[106:107], v[106:107], v[86:87] op_sel_hi:[1,0]
	v_pk_fma_f32 v[108:109], v[10:11], v[102:103], v[14:15]
	ds_read_b128 v[100:103], v63 offset:384
	v_pk_fma_f32 v[106:107], v[8:9], v[106:107], v[12:13]
	v_lshl_add_u64 v[116:117], v[56:57], 0, s[2:3]
	global_store_dwordx4 v[116:117], v[106:109], off
	ds_read_b128 v[104:107], v63 offset:400
	ds_read_b128 v[108:111], v63 offset:416
	ds_read_b128 v[112:115], v63 offset:432
	v_sub_f32_e32 v71, v90, v120
	s_waitcnt lgkmcnt(3)
	v_pk_add_f32 v[90:91], v[100:101], 0 op_sel_hi:[1,0]
	v_pk_mul_f32 v[70:71], v[70:71], v[86:87] op_sel_hi:[1,0]
	v_pk_add_f32 v[90:91], v[90:91], v[102:103]
	v_pk_fma_f32 v[100:101], v[0:1], v[70:71], v[4:5]
	s_waitcnt lgkmcnt(2)
	v_pk_add_f32 v[90:91], v[90:91], v[104:105]
	v_pk_mul_f32 v[86:87], v[118:119], v[86:87] op_sel_hi:[1,0]
	v_pk_add_f32 v[90:91], v[90:91], v[106:107]
	v_pk_fma_f32 v[102:103], v[2:3], v[86:87], v[6:7]
	s_waitcnt lgkmcnt(1)
	v_pk_add_f32 v[90:91], v[90:91], v[108:109]
	global_store_dwordx4 v[116:117], v[100:103], off offset:16
	v_pk_add_f32 v[90:91], v[90:91], v[110:111]
	s_waitcnt lgkmcnt(0)
; __device__ __forceinline__ u32x4 pack8f(f32x4 lo, f32x4 hi) { u32x4 w; w.x = cvtpk(lo[0], lo[1]); w.y = cvtpk(lo[2], lo[3]); w.z = cvtpk(hi[0], hi[1]); w.w = cvtpk(hi[2], hi[3]); return w; }
; template <bool LN1>
; __device__ __forceinline__ void ln_phase(Frame& F, const bf16_t* Yin, const float* ga, const float* be, const float* modf, float* stats, bf16_t* ob16, float* of32) {
;     ...
; #pragma unroll
;             for (int k = 0; k < 8; ++k) {
;                 float s = 0.f, q = 0.f;
; #pragma unroll
;                 for (int ww = 0; ww < 8; ++ww) { const f32x2 p = rd[k * 8 + ww]; s += p[0]; q += p[1]; }
;                 const float mean = s * (1.0f / D), var = fmaxf(q * (1.0f / D) - mean * mean, 0.f), rstd = 1.0f / sqrtf(var + 1e-5f);
;                 const size_t ro = (size_t)(r0 + k) * D + c0;
;                 if (LN1) { if (w == 0 && lane == 0) *(f32x2*)(stats + (size_t)(r0 + k) * 2) = (f32x2){mean, rstd};
;                     const int row = r0 + k; const size_t bo = ((((size_t)(row >> 8) * (D / 64)) + (c0 >> 6)) * 256 + (row & 255)) * 64 + (c0 & 63);
;                     *(u32x4*)(ob16 + bo) = pg8::pack8f((v[k][0] - mean) * rstd * ca[0] + cb[0], (v[k][1] - mean) * rstd * ca[1] + cb[1]); }
;                 else { *(f32x4*)(of32 + ro) = (v[k][0] - mean) * rstd * ca[0] + cb[0]; *(f32x4*)(of32 + ro + 4) = (v[k][1] - mean) * rstd * ca[1] + cb[1]; }
	v_pk_add_f32 v[90:91], v[90:91], v[112:113]
	s_nop 0
	v_pk_add_f32 v[90:91], v[90:91], v[114:115]
	s_nop 0
	v_pk_mul_f32 v[104:105], v[90:91], s[10:11] op_sel_hi:[1,0]
	s_nop 0
	v_fma_f32 v65, -v104, v104, v105
	v_max_f32_e32 v65, 0, v65
	v_add_f32_e32 v65, 0x3727c5ac, v65
	v_mul_f32_e32 v67, 0x4f800000, v65
	v_cmp_gt_f32_e32 vcc, s5, v65
	v_sub_f32_e32 v87, v98, v104
	v_sub_f32_e32 v86, v96, v104
	v_cndmask_b32_e32 v65, v65, v67, vcc
	v_sqrt_f32_e32 v67, v65
	v_sub_f32_e32 v91, v94, v104
	v_sub_f32_e32 v90, v92, v104
	v_sub_f32_e32 v102, v84, v104
	v_add_u32_e32 v69, -1, v67
	v_fma_f32 v73, -v69, v67, v65
	v_cmp_ge_f32_e64 s[2:3], 0, v73
	v_add_u32_e32 v73, 1, v67
	v_sub_f32_e32 v103, v88, v104
	v_cndmask_b32_e64 v69, v67, v69, s[2:3]
	v_fma_f32 v67, -v73, v67, v65
	v_cmp_lt_f32_e64 s[2:3], 0, v67
	v_sub_f32_e32 v75, v74, v104
	v_sub_f32_e32 v74, v62, v104
	v_cndmask_b32_e64 v67, v69, v73, s[2:3]
	v_mul_f32_e32 v69, 0x37800000, v67
	v_cndmask_b32_e32 v67, v67, v69, vcc
	v_cmp_class_f32_e32 vcc, v65, v196
	s_nop 1
	v_cndmask_b32_e32 v65, v67, v65, vcc
	v_div_scale_f32 v67, s[2:3], v65, v65, 1.0
	v_rcp_f32_e32 v69, v67
	s_add_i32 s2, s16, 6
	s_ashr_i32 s3, s2, 31
	s_lshl_b64 s[2:3], s[2:3], 14
	v_fma_f32 v70, -v67, v69, 1.0
	v_fmac_f32_e32 v69, v70, v69
	v_div_scale_f32 v70, vcc, 1.0, v65, 1.0
	v_mul_f32_e32 v71, v70, v69
	v_fma_f32 v73, -v67, v71, v70
	v_fmac_f32_e32 v71, v73, v69
	v_fma_f32 v67, -v67, v71, v70
	v_div_fmas_f32 v67, v67, v69, v71
	v_div_fixup_f32 v70, v67, v65, 1.0
	v_pk_mul_f32 v[86:87], v[86:87], v[70:71] op_sel_hi:[1,0]
	v_pk_mul_f32 v[90:91], v[90:91], v[70:71] op_sel_hi:[1,0]
	v_pk_fma_f32 v[92:93], v[10:11], v[86:87], v[14:15]
	ds_read_b128 v[84:87], v63 offset:448
	v_pk_fma_f32 v[90:91], v[8:9], v[90:91], v[12:13]
	v_lshl_add_u64 v[100:101], v[56:57], 0, s[2:3]
	global_store_dwordx4 v[100:101], v[90:93], off
	ds_read_b128 v[88:91], v63 offset:464
	ds_read_b128 v[92:95], v63 offset:480
	ds_read_b128 v[96:99], v63 offset:496
	s_waitcnt lgkmcnt(3)
	v_pk_add_f32 v[84:85], v[84:85], 0 op_sel_hi:[1,0]
	s_nop 0
	v_pk_add_f32 v[84:85], v[84:85], v[86:87]
	s_waitcnt lgkmcnt(2)
	v_pk_add_f32 v[84:85], v[84:85], v[88:89]
	s_nop 0
	v_pk_add_f32 v[84:85], v[84:85], v[90:91]
	s_waitcnt lgkmcnt(1)
	v_pk_add_f32 v[84:85], v[84:85], v[92:93]
	s_nop 0
	v_pk_add_f32 v[84:85], v[84:85], v[94:95]
	s_waitcnt lgkmcnt(0)
	v_pk_add_f32 v[84:85], v[84:85], v[96:97]
	s_nop 0
	v_pk_add_f32 v[84:85], v[84:85], v[98:99]
	s_nop 0
	v_pk_mul_f32 v[88:89], v[84:85], s[10:11] op_sel_hi:[1,0]
	s_nop 0
	v_fma_f32 v63, -v88, v88, v89
	v_max_f32_e32 v63, 0, v63
	v_add_f32_e32 v63, 0x3727c5ac, v63
	v_mul_f32_e32 v65, 0x4f800000, v63
	v_cmp_gt_f32_e32 vcc, s5, v63
	v_sub_f32_e32 v68, v68, v88
	v_sub_f32_e32 v64, v64, v88
	v_cndmask_b32_e32 v65, v63, v65, vcc
	v_sqrt_f32_e32 v67, v65
	v_pk_mul_f32 v[62:63], v[74:75], v[70:71] op_sel_hi:[1,0]
	v_pk_mul_f32 v[70:71], v[102:103], v[70:71] op_sel_hi:[1,0]
	v_pk_fma_f32 v[84:85], v[0:1], v[62:63], v[4:5]
	v_add_u32_e32 v69, -1, v67
	v_fma_f32 v73, -v69, v67, v65
	v_cmp_ge_f32_e64 s[2:3], 0, v73
	v_add_u32_e32 v73, 1, v67
	v_pk_fma_f32 v[86:87], v[2:3], v[70:71], v[6:7]
	v_cndmask_b32_e64 v69, v67, v69, s[2:3]
	v_fma_f32 v67, -v73, v67, v65
	v_cmp_lt_f32_e64 s[2:3], 0, v67
	v_sub_f32_e32 v71, v82, v88
	v_sub_f32_e32 v75, v78, v88
	v_cndmask_b32_e64 v67, v69, v73, s[2:3]
	v_mul_f32_e32 v69, 0x37800000, v67
	v_cndmask_b32_e32 v67, v67, v69, vcc
	v_cmp_class_f32_e32 vcc, v65, v196
	v_sub_f32_e32 v74, v76, v88
	global_store_dwordx4 v[100:101], v[84:87], off offset:16
	v_cndmask_b32_e32 v65, v67, v65, vcc
	v_div_scale_f32 v67, s[2:3], v65, v65, 1.0
	v_rcp_f32_e32 v69, v67
	s_add_i32 s2, s16, 7
	s_ashr_i32 s3, s2, 31
	s_lshl_b64 s[2:3], s[2:3], 14
	v_fma_f32 v62, -v67, v69, 1.0
	v_fmac_f32_e32 v69, v62, v69
	v_div_scale_f32 v62, vcc, 1.0, v65, 1.0
	v_mul_f32_e32 v63, v62, v69
	v_fma_f32 v70, -v67, v63, v62
	v_fmac_f32_e32 v63, v70, v69
	v_fma_f32 v62, -v67, v63, v62
	v_div_fmas_f32 v62, v62, v69, v63
	v_div_fixup_f32 v62, v62, v65, 1.0
	v_sub_f32_e32 v70, v80, v88
	v_sub_f32_e32 v69, v72, v88
	v_sub_f32_e32 v65, v66, v88
	v_pk_mul_f32 v[74:75], v[74:75], v[62:63] op_sel_hi:[1,0]
	v_pk_mul_f32 v[70:71], v[70:71], v[62:63] op_sel_hi:[1,0]
	v_pk_mul_f32 v[66:67], v[64:65], v[62:63] op_sel_hi:[1,0]
	v_pk_mul_f32 v[62:63], v[68:69], v[62:63] op_sel_hi:[1,0]
	v_pk_fma_f32 v[76:77], v[10:11], v[70:71], v[14:15]
	v_pk_fma_f32 v[74:75], v[8:9], v[74:75], v[12:13]
	v_lshl_add_u64 v[70:71], v[56:57], 0, s[2:3]
	v_pk_fma_f32 v[64:65], v[2:3], v[62:63], v[6:7]
	v_pk_fma_f32 v[62:63], v[0:1], v[66:67], v[4:5]
	s_cmp_eq_u32 s15, 56
	global_store_dwordx4 v[70:71], v[74:77], off
	global_store_dwordx4 v[70:71], v[62:65], off offset:16
	s_cbranch_scc1 .LBB0_1361
